# grid-barrier code deduplicated: textually identical inlined barrier copies share one copy per cluster (return via compare chain), 11k fewer instructions
# baseline (speedup 1.0000x reference)
.LBB0_337:
	s_cmp_gt_i32 s77, 2
	s_cselect_b64 s[0:1], -1, 0
	s_and_b64 s[2:3], s[4:5], s[0:1]
	s_andn2_b64 vcc, exec, s[2:3]
	s_cbranch_vccnz .LBB0_387
	s_mov_b32 vcc_lo, 1
	v_writelane_b32 v255, vcc_lo, 0
	s_branch .Lbar_shared_5
.Lbar_ret_1:
.LBB0_387:
	s_cmp_lt_i32 s76, 3
	s_cselect_b64 s[8:9], -1, 0
	s_and_b64 s[0:1], s[8:9], s[0:1]
	s_andn2_b64 vcc, exec, s[0:1]
	s_cbranch_vccnz .LBB0_647
	s_cmpk_lt_i32 s33, 0x300
	s_movk_i32 s2, 0x800
	s_cselect_b64 s[4:5], -1, 0
	s_cmpk_gt_i32 s33, 0x2ff
	s_mov_b32 s80, -1
	s_cbranch_scc1 .LBB0_390
	s_ashr_i32 s0, s33, 31
	s_lshr_b32 s0, s0, 29
	s_add_i32 s0, s33, s0
	s_ashr_i32 s1, s0, 3
	s_and_b32 s0, s0, -8
	s_sub_i32 s0, s33, s0
	s_cmp_lt_i32 s0, 0
	s_movk_i32 s3, 0x61
	s_cselect_b32 s3, s3, 0x60
	s_mul_i32 s0, s0, s3
	s_add_i32 s0, s0, s1
	s_mul_hi_i32 s1, s0, 0x2aaaaaab
	s_lshr_b32 s3, s1, 31
	s_ashr_i32 s1, s1, 4
	s_add_i32 s1, s1, s3
	s_lshl_b32 s3, s1, 3
	s_mulk_i32 s1, 0x60
	s_sub_i32 s0, s0, s1
	s_bfe_i32 s1, s0, 0x80000
	s_bfe_u32 s1, s1, 0x3000c
	s_add_i32 s1, s0, s1
	s_and_b32 s1, s1, 0xf8
	s_sub_i32 s0, s0, s1
	s_sext_i32_i8 s0, s0
	s_add_i32 s80, s3, s0

.LBB0_647:
	s_cmp_gt_i32 s77, 3
	s_cselect_b64 s[0:1], -1, 0
	s_and_b64 s[2:3], s[8:9], s[0:1]
	s_andn2_b64 vcc, exec, s[2:3]
	s_cbranch_vccnz .LBB0_697
	s_mov_b32 vcc_lo, 2
	v_writelane_b32 v255, vcc_lo, 0
	s_branch .Lbar_shared_5
.Lbar_ret_2:
.LBB0_697:
	s_cmp_lt_i32 s76, 4
	s_cselect_b64 s[4:5], -1, 0
	s_and_b64 s[0:1], s[4:5], s[0:1]
	s_andn2_b64 vcc, exec, s[0:1]
	s_cbranch_vccnz .LBB0_746
	s_cmpk_gt_i32 s33, 0x1ff
	s_cbranch_scc1 .LBB0_746
	s_add_u32 s30, s74, 0x26200000
	s_addc_u32 s31, s75, 0
	s_add_u32 s34, s74, 0x2a200000
	s_addc_u32 s35, s75, 0
	s_add_u32 s36, s74, 0x2b200000
	s_addc_u32 s37, s75, 0
	s_add_u32 s38, s74, 0x22200000
	s_addc_u32 s39, s75, 0
	s_waitcnt lgkmcnt(0)
	s_add_u32 s24, s74, 0x15e00000
	s_addc_u32 s25, s75, 0
	v_lshrrev_b32_e32 v3, 6, v0
	v_lshrrev_b32_e32 v13, 4, v1
	s_mov_b64 s[2:3], src_shared_base
	s_add_u32 s26, s74, 0x16000000
	v_lshl_or_b32 v13, v3, 2, v13
	s_addc_u32 s27, s75, 0
	v_lshlrev_b32_e32 v10, 4, v0
	v_lshlrev_b32_e32 v14, 10, v13
	v_lshlrev_b32_e32 v13, 4, v13
	s_add_i32 s2, 0, 0x1e000
	v_and_b32_e32 v155, 31, v0
	v_and_b32_e32 v7, 0x1c0, v0
	v_and_b32_e32 v15, 0xf0, v10
	v_and_b32_e32 v13, 0x70, v13
	s_cmp_lg_u32 0, -1
	v_lshl_or_b32 v8, v3, 5, v155
	v_bitop3_b32 v132, v13, v14, v15 bitop3:0xde
	v_lshrrev_b32_e32 v13, 4, v0
	v_lshlrev_b32_e32 v140, 10, v3
	v_lshlrev_b32_e32 v159, 16, v3
	v_lshl_add_u32 v3, v7, 2, s2
	s_cselect_b32 s2, 0, 0
	v_and_b32_e32 v13, 16, v13
	v_lshrrev_b32_e32 v15, 1, v0
	v_lshrrev_b32_e32 v16, 5, v0
	s_cselect_b32 s3, s3, 0
	s_add_u32 s2, s2, 0xc000
	v_lshrrev_b32_e32 v5, 5, v1
	v_lshlrev_b32_e32 v9, 3, v0
	v_bfe_u32 v14, v0, 2, 2
	v_and_b32_e32 v15, 8, v15
	v_and_or_b32 v13, v16, 4, v13
	s_addc_u32 s3, s3, 0
	v_and_b32_e32 v11, 0xc0, v10
	v_lshlrev_b32_e32 v12, 1, v0
	v_or3_b32 v13, v13, v14, v15
	v_and_or_b32 v14, v16, 2, v5
	v_and_b32_e32 v15, 48, v10
	v_and_b32_e32 v157, 0x118, v9
	v_lshlrev_b32_e32 v142, 4, v5
	v_lshlrev_b32_e32 v9, 2, v5
	s_cmp_lg_u64 s[2:3], 0
	v_lshlrev_b32_e32 v4, 11, v8
	v_mov_b32_e32 v2, 0
	v_lshlrev_b32_e32 v6, 3, v5
	v_lshl_or_b32 v14, v14, 6, v15
	v_lshlrev_b32_e32 v156, 8, v155
	v_and_or_b32 v158, v12, 32, v11
	v_lshlrev_b32_e32 v5, 13, v5
	v_add_u32_e32 v151, 0, v140
	s_cselect_b32 s2, s2, -1
	v_lshl_add_u32 v153, v155, 2, v3
	v_add_u32_e32 v154, v3, v142
	v_sub_u32_e32 v3, v8, v9
	v_lshl_or_b32 v134, v13, 10, v14
	v_mov_b32_e32 v133, v2
	v_mov_b32_e32 v135, v2
	v_and_b32_e32 v141, 0x70, v10
	v_or_b32_e32 v143, 64, v142
	v_or_b32_e32 v144, 0x80, v142
	v_or_b32_e32 v145, 0xc0, v142
	v_cmp_gt_u32_e64 s[0:1], 32, v1
	v_or_b32_e32 v146, 32, v142
	v_or_b32_e32 v147, 0x60, v142
	v_or_b32_e32 v148, 0xa0, v142
	v_or_b32_e32 v149, 0xe0, v142
	v_or3_b32 v150, v5, v159, v155
	v_add_u32_e32 v152, s2, v156
	v_add3_u32 v160, v157, 0, v158
	v_add_u32_e32 v161, 0x144, v3
	s_lshl_b32 s28, s33, 4
	s_lshl_b32 s29, s96, 4
	v_lshlrev_b32_e32 v138, 1, v4
	v_mov_b32_e32 v139, v2
	v_lshlrev_b32_e32 v136, 1, v6
	v_mov_b32_e32 v137, v2
	v_add_u32_e32 v162, 0xc000, v151
	s_mov_b64 s[6:7], 0x8000
	v_add_u32_e32 v163, 0xe000, v151
	v_add_u32_e32 v164, 0x2000, v151
	s_mov_b64 s[8:9], 0x10000
	s_mov_b64 s[10:11], 0x18000
	s_add_i32 s42, 0, 0x10000
	s_add_i32 s43, 0, 0x12000
	s_movk_i32 s44, 0xfefe
	s_mov_b32 s45, 0x42b504f3
	s_mov_b32 s46, 0x3fb8aa3b
	s_movk_i32 s47, 0x7fff
	v_mov_b32_e32 v165, 0xf149f2ca
	s_mov_b32 s50, s33
	s_branch .LBB0_702

.LBB0_746:
	s_cmp_gt_i32 s77, 4
	s_cselect_b64 s[0:1], -1, 0
	s_and_b64 s[2:3], s[4:5], s[0:1]
	s_andn2_b64 vcc, exec, s[2:3]
	s_cbranch_vccnz .LBB0_796
	s_mov_b32 vcc_lo, 3
	v_writelane_b32 v255, vcc_lo, 0
	s_branch .Lbar_shared_5
.Lbar_ret_3:
.LBB0_796:
	s_cmp_lt_i32 s76, 5
	s_cselect_b64 s[2:3], -1, 0
	s_and_b64 s[0:1], s[2:3], s[0:1]
	s_andn2_b64 vcc, exec, s[0:1]
	s_cbranch_vccnz .LBB0_820
	s_lshl_b32 s0, s33, 3
	v_readlane_b32 s1, v254, 14
	s_waitcnt lgkmcnt(0)
	s_add_i32 s20, s1, s0
	s_cmpk_gt_i32 s20, 0x3fff
	s_cbranch_scc1 .LBB0_820
	v_mov_b32_e32 v67, 0
	v_lshlrev_b32_e32 v2, 4, v1
	v_mov_b32_e32 v3, v67
	v_lshlrev_b32_e32 v66, 3, v1
	v_lshl_add_u64 v[2:3], s[74:75], 0, v[2:3]
	s_mov_b64 s[0:1], 0x22200000
	v_lshl_add_u64 v[68:69], v[2:3], 0, s[0:1]
	v_lshl_add_u64 v[2:3], s[74:75], 0, v[66:67]
	s_mov_b64 s[4:5], 0x51000000
	v_lshl_add_u64 v[70:71], v[2:3], 0, s[4:5]
	v_mbcnt_lo_u32_b32 v2, -1, 0
	v_mbcnt_hi_u32_b32 v2, -1, v2
	v_and_b32_e32 v3, 64, v2
	v_add_u32_e32 v3, 64, v3
	v_xor_b32_e32 v4, 1, v2
	v_cmp_lt_i32_e32 vcc, v4, v3
	s_lshl_b32 s24, s96, 3
	s_add_u32 s25, s74, 0x53000000
	v_cndmask_b32_e32 v4, v2, v4, vcc
	v_lshlrev_b32_e32 v66, 2, v4
	v_xor_b32_e32 v4, 2, v2
	v_cmp_lt_i32_e32 vcc, v4, v3
	s_addc_u32 s26, s75, 0
	v_cmp_eq_u32_e64 s[0:1], 0, v1
	v_cndmask_b32_e32 v4, v2, v4, vcc
	v_lshlrev_b32_e32 v72, 2, v4
	v_xor_b32_e32 v4, 4, v2
	v_cmp_lt_i32_e32 vcc, v4, v3
	s_lshl_b32 s27, s96, 4
	s_mul_i32 s28, s96, 24
	v_cndmask_b32_e32 v4, v2, v4, vcc
	v_lshlrev_b32_e32 v73, 2, v4
	v_xor_b32_e32 v4, 8, v2
	v_cmp_lt_i32_e32 vcc, v4, v3
	s_mov_b32 s29, 0xda24260
	s_mov_b32 s30, 0x42fe0000
	v_cndmask_b32_e32 v4, v2, v4, vcc
	v_lshlrev_b32_e32 v74, 2, v4
	v_xor_b32_e32 v4, 16, v2
	v_cmp_lt_i32_e32 vcc, v4, v3
	s_mov_b32 s31, 0x40c0c00
	s_nop 0
	v_cndmask_b32_e32 v4, v2, v4, vcc
	v_lshlrev_b32_e32 v75, 2, v4
	v_xor_b32_e32 v4, 32, v2
	v_cmp_lt_i32_e32 vcc, v4, v3
	s_nop 1
	v_cndmask_b32_e32 v2, v2, v4, vcc
	v_lshlrev_b32_e32 v76, 2, v2
	s_branch .LBB0_801

.LBB0_820:
	s_cmp_gt_i32 s77, 5
	s_cselect_b64 s[0:1], -1, 0
	s_and_b64 s[2:3], s[2:3], s[0:1]
	s_andn2_b64 vcc, exec, s[2:3]
	s_cbranch_vccnz .LBB0_870
	s_mov_b32 vcc_lo, 4
	v_writelane_b32 v255, vcc_lo, 0
	s_branch .Lbar_shared_5
.Lbar_ret_4:
.LBB0_870:
	s_cmp_lt_i32 s76, 6
	s_cselect_b64 s[10:11], -1, 0
	s_and_b64 s[0:1], s[10:11], s[0:1]
	s_andn2_b64 vcc, exec, s[0:1]
	s_cbranch_vccnz .LBB0_919
	s_cmpk_lt_i32 s33, 0x200
	s_movk_i32 s2, 0x400
	s_cselect_b64 s[0:1], -1, 0
	s_cmpk_gt_i32 s33, 0x1ff
	v_readfirstlane_b32 s6, v0
	s_cbranch_scc1 .LBB0_877
	s_ashr_i32 s3, s33, 31
	s_lshr_b32 s3, s3, 29
	s_add_i32 s3, s33, s3
	s_and_b32 s4, s3, -8
	s_sub_i32 s7, s33, s4
	s_cmp_gt_i32 s7, -1
	s_cbranch_scc0 .LBB0_874
	s_lshl_b32 s8, s7, 6
	s_cbranch_execz .LBB0_875
	s_branch .LBB0_876

.LBB0_919:
	s_cmp_gt_i32 s77, 6
	s_cselect_b64 s[0:1], -1, 0
	s_and_b64 s[2:3], s[10:11], s[0:1]
	s_andn2_b64 vcc, exec, s[2:3]
	s_cbranch_vccnz .LBB0_969
	s_mov_b32 vcc_lo, 5
	v_writelane_b32 v255, vcc_lo, 0
.Lbar_shared_5:
	s_waitcnt vmcnt(0)
	v_cmp_eq_u32_e32 vcc, 0, v0
	s_waitcnt lgkmcnt(0)
	s_barrier
	s_and_saveexec_b64 s[2:3], vcc
	s_cbranch_execz .LBB0_968
	v_readlane_b32 s4, v254, 13
	s_waitcnt vmcnt(0) expcnt(0) lgkmcnt(0)
	s_nop 0
	v_mov_b32_e32 v2, s4
	ds_read_b32 v4, v2
	ds_read_b32 v2, v2 offset:4
	s_waitcnt lgkmcnt(1)
	v_cmp_ne_u32_e32 vcc, 0, v4
	s_cbranch_vccnz .LBB0_936
	v_readlane_b32 s4, v254, 11
	v_readlane_b32 s5, v254, 12
	s_load_dwordx2 s[8:9], s[4:5], 0x4
	s_add_u32 s4, s78, 0x1000
	s_addc_u32 s5, s79, 0
	s_add_u32 s6, s78, 0x1100
	s_addc_u32 s7, s79, 0
	s_waitcnt lgkmcnt(0)
	s_mul_i32 s22, s8, s96
	s_add_u32 s8, s78, 0x1200
	s_mul_i32 s22, s22, s9
	s_addc_u32 s9, s79, 0
	s_add_u32 s10, s78, 0x1300
	s_addc_u32 s11, s79, 0
	s_mov_b32 s23, 1
	v_mov_b32_e32 v18, 0
	s_branch .LBB0_924

.LBB0_968:
	s_or_b64 exec, exec, s[2:3]
	s_waitcnt lgkmcnt(0)
	s_barrier
	v_readlane_b32 vcc_lo, v255, 0
	s_nop 3
	s_cmp_eq_u32 vcc_lo, 1
	s_cbranch_scc1 .Lbar_ret_1
	s_cmp_eq_u32 vcc_lo, 2
	s_cbranch_scc1 .Lbar_ret_2
	s_cmp_eq_u32 vcc_lo, 3
	s_cbranch_scc1 .Lbar_ret_3
	s_cmp_eq_u32 vcc_lo, 4
	s_cbranch_scc1 .Lbar_ret_4
	s_cmp_eq_u32 vcc_lo, 6
	s_cbranch_scc1 .Lbar_ret_6
	s_cmp_eq_u32 vcc_lo, 7
	s_cbranch_scc1 .Lbar_ret_7
	s_cmp_eq_u32 vcc_lo, 8
	s_cbranch_scc1 .Lbar_ret_8

.LBB0_1014:
	s_cmp_gt_i32 s77, 7
	s_cselect_b64 s[0:1], -1, 0
	s_and_b64 s[2:3], s[12:13], s[0:1]
	s_andn2_b64 vcc, exec, s[2:3]
	s_cbranch_vccnz .LBB0_1064
	s_mov_b32 vcc_lo, 6
	v_writelane_b32 v255, vcc_lo, 0
	s_branch .Lbar_shared_5
.Lbar_ret_6:
.LBB0_1064:
	s_cmp_lt_i32 s76, 8
	s_cselect_b64 s[4:5], -1, 0
	s_and_b64 s[0:1], s[4:5], s[0:1]
	s_andn2_b64 vcc, exec, s[0:1]
	s_cbranch_vccnz .LBB0_1095
	s_movk_i32 s0, 0x400
	s_cmpk_gt_i32 s33, 0x7ff
	v_readfirstlane_b32 s26, v0
	s_cbranch_scc1 .LBB0_1095
	s_ashr_i32 s42, s33, 31
	s_lshr_b32 s1, s42, 29
	s_add_i32 s1, s33, s1
	s_and_b32 s2, s1, -8
	s_sub_i32 s6, s33, s2
	s_cmp_gt_i32 s6, -1
	s_cbranch_scc0 .LBB0_1068
	s_lshl_b32 s10, s6, 8
	s_cbranch_execz .LBB0_1069
	s_branch .LBB0_1070

.LBB0_1095:
	s_cmp_gt_i32 s77, 8
	s_cselect_b64 s[0:1], -1, 0
	s_and_b64 s[2:3], s[4:5], s[0:1]
	s_andn2_b64 vcc, exec, s[2:3]
	s_cbranch_vccnz .LBB0_1145
	s_mov_b32 vcc_lo, 7
	v_writelane_b32 v255, vcc_lo, 0
	s_branch .Lbar_shared_5
.Lbar_ret_7:
.LBB0_1145:
	s_cmp_lt_i32 s76, 9
	s_cselect_b64 s[6:7], -1, 0
	s_and_b64 s[0:1], s[6:7], s[0:1]
	s_andn2_b64 vcc, exec, s[0:1]
	s_cbranch_vccnz .LBB0_1193
	s_cmpk_lt_i32 s33, 0x200
	s_movk_i32 s0, 0x2000
	s_cselect_b64 s[2:3], -1, 0
	s_cmpk_gt_i32 s33, 0x1ff
	v_readfirstlane_b32 s34, v0
	s_cbranch_scc1 .LBB0_1152
	s_ashr_i32 s1, s33, 31
	s_lshr_b32 s1, s1, 29
	s_add_i32 s1, s33, s1
	s_and_b32 s4, s1, -8
	s_sub_i32 s8, s33, s4
	s_cmp_gt_i32 s8, -1
	s_cbranch_scc0 .LBB0_1149
	s_lshl_b32 s9, s8, 6
	s_cbranch_execz .LBB0_1150
	s_branch .LBB0_1151

.LBB0_1193:
	s_cmp_gt_i32 s77, 9
	s_cselect_b64 s[0:1], -1, 0
	s_and_b64 s[2:3], s[6:7], s[0:1]
	s_andn2_b64 vcc, exec, s[2:3]
	s_cbranch_vccnz .LBB0_1243
	s_mov_b32 vcc_lo, 8
	v_writelane_b32 v255, vcc_lo, 0
	s_branch .Lbar_shared_5
.Lbar_ret_8:
.LBB0_1243:
	s_cmp_lt_i32 s76, 10
	s_cselect_b64 s[4:5], -1, 0
	s_and_b64 s[0:1], s[4:5], s[0:1]
	s_andn2_b64 vcc, exec, s[0:1]
	s_cbranch_vccnz .LBB0_1315
	s_cmpk_lt_i32 s33, 0x100
	s_movk_i32 s2, 0x800
	s_cselect_b64 s[6:7], -1, 0
	s_cmpk_gt_i32 s33, 0xff
	s_mov_b32 s36, -1
	s_cbranch_scc1 .LBB0_1250
	s_ashr_i32 s0, s33, 31
	s_lshr_b32 s0, s0, 29
	s_add_i32 s3, s33, s0
	s_and_b32 s0, s3, -8
	s_sub_i32 s8, s33, s0
	s_cmp_gt_i32 s8, -1
	s_cbranch_scc0 .LBB0_1247
	s_lshl_b32 s9, s8, 5
	s_cbranch_execz .LBB0_1248
	s_branch .LBB0_1249

.LBB0_1521:
	s_cmp_gt_i32 s77, 12
	s_cselect_b64 s[0:1], -1, 0
	s_and_b64 s[2:3], s[4:5], s[0:1]
	s_andn2_b64 vcc, exec, s[2:3]
	s_cbranch_vccnz .LBB0_1571
	s_mov_b32 vcc_lo, 11
	v_writelane_b32 v255, vcc_lo, 0
	s_branch .Lbar_shared_15
.Lbar_ret_11:
.LBB0_1571:
	s_cmp_lt_i32 s76, 13
	s_cselect_b64 s[4:5], -1, 0
	s_and_b64 s[0:1], s[4:5], s[0:1]
	s_andn2_b64 vcc, exec, s[0:1]
	s_cbranch_vccnz .LBB0_1605
	s_cmpk_gt_i32 s33, 0x1ff
	s_cbranch_scc1 .LBB0_1605
	v_lshrrev_b32_e32 v142, 6, v0
	v_lshrrev_b32_e32 v143, 4, v1
	v_lshlrev_b32_e32 v12, 4, v0
	v_lshl_or_b32 v14, v142, 2, v143
	s_add_u32 s28, s74, 0x2be00000
	v_lshrrev_b32_e32 v152, 5, v1
	v_lshrrev_b32_e32 v6, 1, v0
	v_lshlrev_b32_e32 v15, 12, v14
	v_and_b32_e32 v16, 0xf0, v12
	v_lshlrev_b32_e32 v14, 4, v14
	s_movk_i32 s0, 0x70
	s_addc_u32 s29, s75, 0
	v_bitop3_b32 v7, v152, v6, 7 bitop3:0x78
	v_and_b32_e32 v17, 0x70, v14
	v_bitop3_b32 v147, v14, v16, s0 bitop3:0x6c
	v_lshrrev_b32_e32 v14, 4, v0
	v_and_b32_e32 v148, 8, v6
	v_lshrrev_b32_e32 v6, 5, v0
	s_add_u32 s30, s74, 0x31e00000
	v_and_b32_e32 v145, 16, v14
	v_and_b32_e32 v149, 4, v6
	s_addc_u32 s31, s75, 0
	v_bfe_u32 v146, v0, 2, 2
	v_or_b32_e32 v14, v149, v145
	v_and_or_b32 v6, v6, 2, v152
	v_and_b32_e32 v150, 48, v12
	s_add_u32 s34, s74, 0x36200000
	v_or3_b32 v14, v14, v146, v148
	v_lshl_or_b32 v6, v6, 6, v150
	v_lshrrev_b32_e32 v141, 3, v1
	s_addc_u32 s35, s75, 0
	v_lshl_or_b32 v134, v14, 12, v6
	v_lshl_or_b32 v6, v142, 3, v141
	s_add_u32 s36, s74, 0x2bb00000
	v_lshrrev_b32_e32 v14, 1, v6
	s_addc_u32 s37, s75, 0
	v_xor_b32_e32 v14, v14, v0
	s_mov_b64 s[2:3], src_shared_base
	s_add_u32 s38, s74, 0x22200000
	v_lshlrev_b32_e32 v14, 4, v14
	s_addc_u32 s39, s75, 0
	v_and_b32_e32 v4, 0x1c0, v0
	v_lshlrev_b32_e32 v11, 3, v0
	v_and_b32_e32 v13, 0xc0, v12
	v_lshlrev_b32_e32 v144, 1, v0
	v_and_b32_e32 v151, 0x70, v14
	s_add_i32 s2, 0, 0x1e000
	s_waitcnt lgkmcnt(0)
	v_and_b32_e32 v3, 31, v0
	v_lshl_or_b32 v136, v6, 7, v151
	v_and_b32_e32 v6, 0x118, v11
	v_and_b32_e32 v157, 0x70, v12
	v_and_or_b32 v11, v144, 32, v13
	v_lshlrev_b32_e32 v12, 13, v152
	v_lshlrev_b32_e32 v13, 16, v142
	v_lshl_add_u32 v4, v4, 2, s2
	s_add_i32 s2, 0, 0x1e800
	v_or3_b32 v166, v12, v13, v3
	v_lshl_add_u32 v12, v142, 12, s2
	s_add_i32 s2, 0, 0x18000
	s_cmp_lg_u32 0, -1
	v_lshlrev_b32_e32 v182, 10, v142
	s_cselect_b32 s8, 0, 0
	v_add_u32_e32 v168, s2, v182
	s_cselect_b32 s6, s3, 0
	s_add_u32 s2, s8, 0xc000
	s_addc_u32 s3, s6, 0
	s_cmp_lg_u64 s[2:3], 0
	s_cselect_b32 s2, s2, -1
	v_lshl_add_u32 v169, v3, 8, s2
	s_add_u32 s2, s8, 0x18000
	v_bfe_u32 v153, v0, 1, 3
	s_addc_u32 s3, s6, 0
	v_lshl_or_b32 v2, v142, 5, v3
	v_bitop3_b32 v8, v152, v153, 2 bitop3:0x36
	v_bitop3_b32 v9, v152, v153, 4 bitop3:0x36
	v_bitop3_b32 v10, v152, v153, 6 bitop3:0x36
	s_cmp_lg_u64 s[2:3], 0
	v_mul_u32_u24_e32 v140, 0xc00, v2
	v_mov_b32_e32 v131, 0
	v_lshlrev_b32_e32 v2, 3, v152
	v_lshlrev_b32_e32 v5, 7, v3
	v_lshlrev_b32_e32 v158, 4, v152
	v_lshl_add_u32 v7, v7, 4, v12
	v_lshl_add_u32 v8, v8, 4, v12
	v_lshl_add_u32 v9, v9, 4, v12
	v_lshl_add_u32 v10, v10, 4, v12
	s_cselect_b32 s2, s2, -1
	v_or_b32_e32 v154, 2, v152
	v_or_b32_e32 v155, 4, v152
	v_or_b32_e32 v156, 6, v152
	v_bitop3_b32 v132, v17, v15, v16 bitop3:0xde
	v_mov_b32_e32 v133, v131
	v_mov_b32_e32 v135, v131
	v_mov_b32_e32 v137, v131
	v_or_b32_e32 v159, 64, v158
	v_or_b32_e32 v160, 0x80, v158
	v_or_b32_e32 v161, 0xc0, v158
	v_cmp_gt_u32_e64 s[0:1], 32, v1
	v_or_b32_e32 v162, 32, v158
	v_or_b32_e32 v163, 0x60, v158
	v_or_b32_e32 v164, 0xa0, v158
	v_or_b32_e32 v165, 0xe0, v158
	s_mov_b32 s7, 0
	v_add_u32_e32 v167, 0, v182
	v_add_u32_e32 v170, s2, v5
	v_add_u32_e32 v171, v12, v5
	v_lshl_add_u32 v172, v3, 2, v4
	v_add_u32_e32 v173, v4, v158
	v_add3_u32 v174, v6, 0, v11
	v_lshlrev_b32_e32 v138, 1, v2
	s_mov_b64 s[8:9], 0x20000
	s_mov_b64 s[10:11], 0x40000
	s_add_i32 s42, 0, 0x10000
	s_mov_b64 s[12:13], 0x60000
	s_add_i32 s43, 0, 0x12000
	s_mov_b64 s[14:15], 0x2000
	s_add_i32 s44, 0, 0x1a000
	s_mov_b32 s45, 0x42ddb3d8
	v_mov_b32_e32 v183, 0xf149f2ca
	s_movk_i32 s46, 0x7fff
	v_add_u32_e32 v175, v7, v5
	v_add_u32_e32 v176, v8, v5
	v_add_u32_e32 v177, v9, v5
	v_add_u32_e32 v178, v10, v5
	s_mov_b32 s47, s33
	s_branch .LBB0_1575

.LBB0_1605:
	s_cmp_gt_i32 s77, 13
	s_cselect_b64 s[0:1], -1, 0
	s_and_b64 s[2:3], s[4:5], s[0:1]
	s_andn2_b64 vcc, exec, s[2:3]
	s_cbranch_vccnz .LBB0_1655
	s_mov_b32 vcc_lo, 12
	v_writelane_b32 v255, vcc_lo, 0
	s_branch .Lbar_shared_15
.Lbar_ret_12:
.LBB0_1655:
	s_cmp_lt_i32 s76, 14
	s_cselect_b64 s[2:3], -1, 0
	s_and_b64 s[0:1], s[2:3], s[0:1]
	s_andn2_b64 vcc, exec, s[0:1]
	s_cbranch_vccnz .LBB0_1679
	s_lshl_b32 s0, s33, 3
	v_readlane_b32 s1, v254, 14
	s_add_i32 s16, s1, s0
	s_cmpk_gt_i32 s16, 0x3fff
	s_cbranch_scc1 .LBB0_1679
	v_mov_b32_e32 v67, 0
	v_lshlrev_b32_e32 v2, 4, v1
	s_waitcnt lgkmcnt(0)
	v_mov_b32_e32 v3, v67
	v_lshlrev_b32_e32 v66, 3, v1
	v_lshl_add_u64 v[2:3], s[74:75], 0, v[2:3]
	s_mov_b64 s[0:1], 0x22200000
	v_lshl_add_u64 v[68:69], v[2:3], 0, s[0:1]
	v_lshl_add_u64 v[2:3], s[74:75], 0, v[66:67]
	s_mov_b64 s[4:5], 0x51000000
	v_lshl_add_u64 v[70:71], v[2:3], 0, s[4:5]
	v_mbcnt_lo_u32_b32 v2, -1, 0
	v_mbcnt_hi_u32_b32 v2, -1, v2
	v_and_b32_e32 v3, 64, v2
	v_add_u32_e32 v3, 64, v3
	v_xor_b32_e32 v4, 1, v2
	v_cmp_lt_i32_e32 vcc, v4, v3
	s_lshl_b32 s20, s96, 3
	s_add_u32 s21, s74, 0x53000000
	v_cndmask_b32_e32 v4, v2, v4, vcc
	v_lshlrev_b32_e32 v66, 2, v4
	v_xor_b32_e32 v4, 2, v2
	v_cmp_lt_i32_e32 vcc, v4, v3
	s_addc_u32 s22, s75, 0
	v_cmp_eq_u32_e64 s[0:1], 0, v1
	v_cndmask_b32_e32 v4, v2, v4, vcc
	v_lshlrev_b32_e32 v72, 2, v4
	v_xor_b32_e32 v4, 4, v2
	v_cmp_lt_i32_e32 vcc, v4, v3
	s_lshl_b32 s23, s96, 4
	s_mul_i32 s24, s96, 24
	v_cndmask_b32_e32 v4, v2, v4, vcc
	v_lshlrev_b32_e32 v73, 2, v4
	v_xor_b32_e32 v4, 8, v2
	v_cmp_lt_i32_e32 vcc, v4, v3
	s_mov_b32 s25, 0xda24260
	s_mov_b32 s26, 0x42fe0000
	v_cndmask_b32_e32 v4, v2, v4, vcc
	v_lshlrev_b32_e32 v74, 2, v4
	v_xor_b32_e32 v4, 16, v2
	v_cmp_lt_i32_e32 vcc, v4, v3
	s_mov_b32 s27, 0x40c0c00
	s_nop 0
	v_cndmask_b32_e32 v4, v2, v4, vcc
	v_lshlrev_b32_e32 v75, 2, v4
	v_xor_b32_e32 v4, 32, v2
	v_cmp_lt_i32_e32 vcc, v4, v3
	s_nop 1
	v_cndmask_b32_e32 v2, v2, v4, vcc
	v_lshlrev_b32_e32 v76, 2, v2
	s_branch .LBB0_1660

.LBB0_1679:
	s_cmp_gt_i32 s77, 14
	s_cselect_b64 s[0:1], -1, 0
	s_and_b64 s[2:3], s[2:3], s[0:1]
	s_andn2_b64 vcc, exec, s[2:3]
	s_cbranch_vccnz .LBB0_1729
	s_mov_b32 vcc_lo, 13
	v_writelane_b32 v255, vcc_lo, 0
	s_branch .Lbar_shared_15
.Lbar_ret_13:
.LBB0_1729:
	s_cmp_lt_i32 s76, 15
	s_cselect_b64 s[6:7], -1, 0
	s_and_b64 s[0:1], s[6:7], s[0:1]
	s_andn2_b64 vcc, exec, s[0:1]
	s_cbranch_vccnz .LBB0_1778
	s_cmpk_lt_i32 s33, 0x200
	s_movk_i32 s2, 0x400
	s_cselect_b64 s[0:1], -1, 0
	s_cmpk_gt_i32 s33, 0x1ff
	v_readfirstlane_b32 s36, v0
	s_cbranch_scc1 .LBB0_1736
	s_ashr_i32 s3, s33, 31
	s_lshr_b32 s3, s3, 29
	s_add_i32 s3, s33, s3
	s_and_b32 s4, s3, -8
	s_sub_i32 s8, s33, s4
	s_cmp_gt_i32 s8, -1
	s_cbranch_scc0 .LBB0_1733
	s_lshl_b32 s9, s8, 6
	s_cbranch_execz .LBB0_1734
	s_branch .LBB0_1735

.LBB0_1778:
	s_cmp_gt_i32 s77, 15
	s_cselect_b64 s[0:1], -1, 0
	s_and_b64 s[2:3], s[6:7], s[0:1]
	s_andn2_b64 vcc, exec, s[2:3]
	s_cbranch_vccnz .LBB0_1828
	s_mov_b32 vcc_lo, 14
	v_writelane_b32 v255, vcc_lo, 0
	s_branch .Lbar_shared_15
.Lbar_ret_14:
.LBB0_1828:
	s_cmp_lt_i32 s76, 16
	s_cselect_b64 s[12:13], -1, 0
	s_and_b64 s[0:1], s[12:13], s[0:1]
	s_andn2_b64 vcc, exec, s[0:1]
	s_cbranch_vccnz .LBB0_1866
	s_lshl_b32 s0, s33, 3
	v_readlane_b32 s1, v254, 14
	s_add_i32 s14, s1, s0
	s_cmpk_gt_i32 s14, 0x3fff
	s_cbranch_scc1 .LBB0_1866
	v_lshlrev_b32_e32 v66, 2, v1
	v_mov_b32_e32 v67, 0
	s_waitcnt lgkmcnt(0)
	v_lshl_add_u64 v[2:3], s[74:75], 0, v[66:67]
	s_mov_b64 s[2:3], 0x4bc00000
	v_lshl_add_u64 v[68:69], v[2:3], 0, s[2:3]
	s_mov_b64 s[2:3], 0x4cc00000
	v_lshlrev_b32_e32 v4, 4, v1
	v_mov_b32_e32 v5, v67
	v_lshl_add_u64 v[70:71], v[2:3], 0, s[2:3]
	v_lshlrev_b32_e32 v2, 3, v1
	v_mov_b32_e32 v3, v67
	v_lshl_add_u64 v[6:7], s[74:75], 0, v[4:5]
	s_mov_b64 s[2:3], 0x1e200000
	v_lshl_add_u64 v[72:73], v[6:7], 0, s[2:3]
	v_lshl_add_u64 v[6:7], s[74:75], 0, v[2:3]
	v_mbcnt_lo_u32_b32 v3, -1, 0
	v_mbcnt_hi_u32_b32 v3, -1, v3
	s_mov_b64 s[6:7], 0x4d700000
	v_and_b32_e32 v5, 64, v3
	v_lshl_add_u64 v[74:75], v[6:7], 0, s[6:7]
	v_add_u32_e32 v5, 64, v5
	v_xor_b32_e32 v6, 1, v3
	v_cmp_lt_i32_e32 vcc, v6, v5
	s_lshl_b32 s38, s96, 3
	s_add_u32 s39, s74, 0x4d610000
	v_cndmask_b32_e32 v6, v3, v6, vcc
	v_lshlrev_b32_e32 v82, 2, v6
	v_xor_b32_e32 v6, 2, v3
	v_cmp_lt_i32_e32 vcc, v6, v5
	s_addc_u32 s42, s75, 0
	s_lshl_b32 s16, s96, 5
	v_cndmask_b32_e32 v6, v3, v6, vcc
	v_lshlrev_b32_e32 v83, 2, v6
	v_xor_b32_e32 v6, 4, v3
	v_cmp_lt_i32_e32 vcc, v6, v5
	s_ashr_i32 s15, s14, 31
	s_lshl_b64 s[6:7], s[14:15], 7
	v_cndmask_b32_e32 v6, v3, v6, vcc
	v_lshlrev_b32_e32 v84, 2, v6
	v_xor_b32_e32 v6, 8, v3
	v_cmp_lt_i32_e32 vcc, v6, v5
	s_ashr_i32 s17, s16, 31
	v_lshl_add_u64 v[76:77], s[6:7], 0, v[66:67]
	v_cndmask_b32_e32 v6, v3, v6, vcc
	v_lshlrev_b32_e32 v85, 2, v6
	v_xor_b32_e32 v6, 16, v3
	v_cmp_lt_i32_e32 vcc, v6, v5
	s_lshl_b64 s[18:19], s[16:17], 7
	s_lshl_b64 s[6:7], s[14:15], 2
	v_cndmask_b32_e32 v6, v3, v6, vcc
	v_lshlrev_b32_e32 v86, 2, v6
	v_xor_b32_e32 v6, 32, v3
	s_add_u32 s43, s6, 0x4d610000
	v_cmp_lt_i32_e32 vcc, v6, v5
	s_addc_u32 s44, s7, 0
	s_lshl_b64 s[6:7], s[14:15], 11
	v_cndmask_b32_e32 v3, v3, v6, vcc
	v_or_b32_e32 v78, s6, v2
	v_mov_b32_e32 v79, s7
	s_lshl_b64 s[6:7], s[14:15], 12
	v_cmp_gt_u32_e64 s[0:1], 32, v1
	v_cmp_eq_u32_e64 s[2:3], 0, v1
	v_cmp_ne_u32_e64 s[4:5], 0, v1
	v_lshlrev_b32_e32 v87, 2, v3
	s_lshl_b64 s[20:21], s[16:17], 2
	s_lshl_b64 s[22:23], s[16:17], 11
	v_or_b32_e32 v80, s6, v4
	v_mov_b32_e32 v81, s7
	s_lshl_b64 s[24:25], s[16:17], 12
	s_lshl_b32 s15, s96, 4
	s_mul_i32 s17, s96, 24
	s_mov_b32 s45, 0xda24260
	v_mov_b32_e32 v66, 0x358637bd
	s_mov_b32 s46, 0x800000
	s_mov_b32 s47, 0x42fe0000
	s_movk_i32 s50, 0xff81
	s_mov_b32 s51, 0x40c0c00
	s_mov_b32 s54, 0x4d700000
	v_mov_b32_e32 v88, 0x7f
	s_branch .LBB0_1833

.LBB0_1866:
	s_cmp_gt_i32 s77, 16
	s_cselect_b64 s[0:1], -1, 0
	s_and_b64 s[2:3], s[12:13], s[0:1]
	s_andn2_b64 vcc, exec, s[2:3]
	s_cbranch_vccnz .LBB0_1916
	s_mov_b32 vcc_lo, 15
	v_writelane_b32 v255, vcc_lo, 0
.Lbar_shared_15:
	s_waitcnt vmcnt(0)
	v_cmp_eq_u32_e32 vcc, 0, v0
	s_waitcnt vmcnt(0) lgkmcnt(0)
	s_barrier
	s_and_saveexec_b64 s[2:3], vcc
	s_cbranch_execz .LBB0_1915
	v_readlane_b32 s4, v254, 13
	s_waitcnt vmcnt(0) expcnt(0) lgkmcnt(0)
	s_nop 0
	v_mov_b32_e32 v2, s4
	ds_read_b32 v4, v2
	ds_read_b32 v2, v2 offset:4
	s_waitcnt lgkmcnt(1)
	v_cmp_ne_u32_e32 vcc, 0, v4
	s_cbranch_vccnz .LBB0_1883
	v_readlane_b32 s4, v254, 11
	v_readlane_b32 s5, v254, 12
	s_load_dwordx2 s[8:9], s[4:5], 0x4
	s_add_u32 s4, s78, 0x1000
	s_addc_u32 s5, s79, 0
	s_add_u32 s6, s78, 0x1100
	s_addc_u32 s7, s79, 0
	s_waitcnt lgkmcnt(0)
	s_mul_i32 s18, s8, s96
	s_add_u32 s8, s78, 0x1200
	s_mul_i32 s18, s18, s9
	s_addc_u32 s9, s79, 0
	s_add_u32 s10, s78, 0x1300
	s_addc_u32 s11, s79, 0
	s_mov_b32 s19, 1
	v_mov_b32_e32 v18, 0
	s_branch .LBB0_1871

.LBB0_1915:
	s_or_b64 exec, exec, s[2:3]
	s_waitcnt lgkmcnt(0)
	s_barrier
	v_readlane_b32 vcc_lo, v255, 0
	s_nop 3
	s_cmp_eq_u32 vcc_lo, 11
	s_cbranch_scc1 .Lbar_ret_11
	s_cmp_eq_u32 vcc_lo, 12
	s_cbranch_scc1 .Lbar_ret_12
	s_cmp_eq_u32 vcc_lo, 13
	s_cbranch_scc1 .Lbar_ret_13
	s_cmp_eq_u32 vcc_lo, 14
	s_cbranch_scc1 .Lbar_ret_14
	s_cmp_eq_u32 vcc_lo, 16
	s_cbranch_scc1 .Lbar_ret_16
	s_cmp_eq_u32 vcc_lo, 17
	s_cbranch_scc1 .Lbar_ret_17
	s_cmp_eq_u32 vcc_lo, 18
	s_cbranch_scc1 .Lbar_ret_18

.LBB0_1947:
	s_cmp_gt_i32 s77, 17
	s_cselect_b64 s[0:1], -1, 0
	s_and_b64 s[2:3], s[4:5], s[0:1]
	s_andn2_b64 vcc, exec, s[2:3]
	s_cbranch_vccnz .LBB0_1997
	s_mov_b32 vcc_lo, 16
	v_writelane_b32 v255, vcc_lo, 0
	s_branch .Lbar_shared_15
.Lbar_ret_16:
.LBB0_1997:
	s_cmp_lt_i32 s76, 18
	s_cselect_b64 s[6:7], -1, 0
	s_and_b64 s[0:1], s[6:7], s[0:1]
	s_andn2_b64 vcc, exec, s[0:1]
	s_cbranch_vccnz .LBB0_2045
	s_cmpk_lt_i32 s33, 0x200
	s_movk_i32 s0, 0x2000
	s_cselect_b64 s[2:3], -1, 0
	s_cmpk_gt_i32 s33, 0x1ff
	v_readfirstlane_b32 s28, v0
	s_cbranch_scc1 .LBB0_2004
	s_ashr_i32 s1, s33, 31
	s_lshr_b32 s1, s1, 29
	s_add_i32 s1, s33, s1
	s_and_b32 s4, s1, -8
	s_sub_i32 s8, s33, s4
	s_cmp_gt_i32 s8, -1
	s_cbranch_scc0 .LBB0_2001
	s_lshl_b32 s9, s8, 6
	s_cbranch_execz .LBB0_2002
	s_branch .LBB0_2003

.LBB0_2045:
	s_cmp_gt_i32 s77, 18
	s_cselect_b64 s[0:1], -1, 0
	s_and_b64 s[2:3], s[6:7], s[0:1]
	s_andn2_b64 vcc, exec, s[2:3]
	s_cbranch_vccnz .LBB0_2095
	s_mov_b32 vcc_lo, 17
	v_writelane_b32 v255, vcc_lo, 0
	s_branch .Lbar_shared_15
.Lbar_ret_17:
.LBB0_2095:
	s_cmp_lt_i32 s76, 19
	s_cselect_b64 s[8:9], -1, 0
	s_and_b64 s[0:1], s[8:9], s[0:1]
	s_andn2_b64 vcc, exec, s[0:1]
	s_cbranch_vccnz .LBB0_2414
	s_cmpk_lt_i32 s33, 0x600
	s_movk_i32 s2, 0x800
	s_cselect_b64 s[4:5], -1, 0
	s_cmpk_gt_i32 s33, 0x5ff
	s_mov_b32 s39, -1
	s_cbranch_scc1 .LBB0_2098
	s_ashr_i32 s0, s33, 31
	s_lshr_b32 s0, s0, 29
	s_add_i32 s0, s33, s0
	s_ashr_i32 s1, s0, 3
	s_and_b32 s0, s0, -8
	s_sub_i32 s0, s33, s0
	s_cmp_lt_i32 s0, 0
	s_movk_i32 s3, 0xc1
	s_cselect_b32 s3, s3, 0xc0
	s_mul_i32 s0, s0, s3
	s_add_i32 s0, s0, s1
	s_mul_hi_i32 s1, s0, 0x2aaaaaab
	s_lshr_b32 s3, s1, 31
	s_ashr_i32 s1, s1, 5
	s_add_i32 s1, s1, s3
	s_lshl_b32 s3, s1, 3
	s_mulk_i32 s1, 0xc0
	s_sub_i32 s0, s0, s1
	s_bfe_u32 s1, s0, 0x3001c
	s_add_i32 s1, s0, s1
	s_and_b32 s1, s1, 0xfff8
	s_sub_i32 s0, s0, s1
	s_sext_i32_i16 s0, s0
	s_add_i32 s39, s3, s0

.LBB0_2414:
	s_cmp_gt_i32 s77, 19
	s_cselect_b64 s[0:1], -1, 0
	s_and_b64 s[2:3], s[8:9], s[0:1]
	s_andn2_b64 vcc, exec, s[2:3]
	s_cbranch_vccnz .LBB0_2464
	s_mov_b32 vcc_lo, 18
	v_writelane_b32 v255, vcc_lo, 0
	s_branch .Lbar_shared_15
.Lbar_ret_18:
.LBB0_2464:
	s_cmp_lt_i32 s76, 20
	s_cselect_b64 s[2:3], -1, 0
	v_writelane_b32 v254, s2, 26
	s_and_b64 s[0:1], s[2:3], s[0:1]
	s_andn2_b64 vcc, exec, s[0:1]
	v_writelane_b32 v254, s3, 27
	s_cbranch_vccnz .LBB0_2482
	s_cmpk_gt_i32 s33, 0x7ff
	s_cbranch_scc1 .LBB0_2482
	s_add_u32 s44, s74, 0x26200000
	s_addc_u32 s45, s75, 0
	s_add_u32 s46, s74, 0x28200000
	s_addc_u32 s47, s75, 0
	s_add_u32 s0, s74, 0x32200000
	s_addc_u32 s1, s75, 0
	v_writelane_b32 v254, s0, 24
	s_lshl_b32 s57, s33, 3
	s_and_b32 s4, s57, 0xffffffc0
	v_writelane_b32 v254, s1, 25
	s_lshl_b32 s0, s33, 7
	v_lshlrev_b32_e32 v6, 3, v0
	v_lshrrev_b32_e32 v64, 5, v0
	s_and_b32 s0, s0, 0x300
	v_and_b32_e32 v59, 0xf8, v6
	v_or_b32_e32 v2, s4, v64
	v_or_b32_e32 v4, s0, v59
	s_waitcnt lgkmcnt(0)
	v_ashrrev_i32_e32 v3, 31, v2
	v_lshlrev_b64 v[2:3], 11, v[2:3]
	v_lshlrev_b32_e32 v7, 1, v4
	v_or_b32_e32 v2, v2, v7
	v_lshl_add_u64 v[4:5], s[44:45], 0, v[2:3]
	v_lshl_add_u64 v[2:3], s[46:47], 0, v[2:3]
	global_load_dwordx4 v[20:23], v[4:5], off
	global_load_dwordx4 v[24:27], v[2:3], off
	v_or_b32_e32 v2, 0x200, v0
	v_lshrrev_b32_e32 v65, 5, v2
	v_or_b32_e32 v2, s4, v65
	v_ashrrev_i32_e32 v3, 31, v2
	v_lshlrev_b64 v[2:3], 11, v[2:3]
	v_or_b32_e32 v2, v2, v7
	v_lshl_add_u64 v[4:5], s[44:45], 0, v[2:3]
	v_lshl_add_u64 v[2:3], s[46:47], 0, v[2:3]
	v_or_b32_e32 v66, 32, v64
	global_load_dwordx4 v[28:31], v[4:5], off
	global_load_dwordx4 v[32:35], v[2:3], off
	v_or_b32_e32 v2, s4, v66
	v_ashrrev_i32_e32 v3, 31, v2
	v_lshlrev_b64 v[2:3], 11, v[2:3]
	v_or_b32_e32 v2, v2, v7
	v_lshl_add_u64 v[4:5], s[44:45], 0, v[2:3]
	v_lshl_add_u64 v[2:3], s[46:47], 0, v[2:3]
	global_load_dwordx4 v[36:39], v[4:5], off
	global_load_dwordx4 v[40:43], v[2:3], off
	v_or_b32_e32 v2, 0x600, v0
	v_lshrrev_b32_e32 v67, 5, v2
	v_or_b32_e32 v2, s4, v67
	v_ashrrev_i32_e32 v3, 31, v2
	v_lshlrev_b64 v[2:3], 11, v[2:3]
	v_or_b32_e32 v2, v2, v7
	v_lshl_add_u64 v[4:5], s[44:45], 0, v[2:3]
	v_lshl_add_u64 v[2:3], s[46:47], 0, v[2:3]
	global_load_dwordx4 v[44:47], v[4:5], off
	global_load_dwordx4 v[48:51], v[2:3], off
	s_movk_i32 s0, 0x100
	s_movk_i32 s2, 0xff
	v_cmp_gt_u32_e64 s[0:1], s0, v0
	v_cmp_lt_u32_e32 vcc, s2, v0
	s_and_saveexec_b64 s[2:3], vcc
	s_xor_b64 s[2:3], exec, s[2:3]
	v_lshlrev_b32_e32 v2, 2, v0
	v_and_b32_e32 v56, 12, v2
	v_mov_b32_e32 v57, 0
	s_or_saveexec_b64 s[2:3], s[2:3]
	v_mov_b32_e32 v3, 0
	v_mov_b32_e32 v4, v3
	v_mov_b32_e32 v5, v3
	v_mov_b32_e32 v2, v3
	v_mov_b64_e32 v[54:55], v[4:5]
	v_lshrrev_b32_e32 v68, 2, v0
	s_mov_b32 s55, 0
	v_mov_b64_e32 v[52:53], v[2:3]
	s_xor_b64 exec, exec, s[2:3]
	s_cbranch_execz .LBB0_2470
	v_or_b32_e32 v4, s4, v68
	v_ashrrev_i32_e32 v5, 31, v4
	v_readlane_b32 s4, v254, 24
	v_lshlrev_b64 v[4:5], 7, v[4:5]
	v_readlane_b32 s5, v254, 25
	v_lshlrev_b32_e32 v2, 2, v0
	v_and_b32_e32 v56, 12, v2
	v_lshl_add_u64 v[4:5], s[4:5], 0, v[4:5]
	s_lshl_b32 s4, s33, 6
	s_and_b32 s54, s4, 64
	v_mov_b32_e32 v57, 0
	v_lshl_add_u64 v[4:5], v[4:5], 0, s[54:55]
	v_lshlrev_b32_e32 v8, 2, v56
	v_mov_b32_e32 v9, v57
	v_lshl_add_u64 v[4:5], v[4:5], 0, v[8:9]
	global_load_dwordx4 v[52:55], v[4:5], off

.LBB0_2482:
	s_cmp_gt_i32 s77, 20
	v_readlane_b32 s2, v254, 26
	s_cselect_b64 s[0:1], -1, 0
	v_readlane_b32 s3, v254, 27
	s_and_b64 s[2:3], s[2:3], s[0:1]
	s_andn2_b64 vcc, exec, s[2:3]
	s_cbranch_vccnz .LBB0_2532
	s_mov_b32 vcc_lo, 19
	v_writelane_b32 v255, vcc_lo, 0
	s_branch .Lbar_shared_23
.Lbar_ret_19:
.LBB0_2532:
	s_cmp_lt_i32 s76, 21
	s_cselect_b64 s[2:3], -1, 0
	s_and_b64 s[0:1], s[2:3], s[0:1]
	s_andn2_b64 vcc, exec, s[0:1]
	s_cbranch_vccnz .LBB0_2555
	s_lshl_b32 s0, s33, 2
	s_and_b32 s0, s0, 28
	s_and_b32 s1, s33, 0xffffffe0
	s_or_b32 s0, s0, s1
	s_bfe_u32 s1, s33, 0x20003
	s_or_b32 s0, s0, s1
	s_cmpk_eq_i32 s96, 0x100
	s_cselect_b32 s18, s0, s33
	s_cmpk_gt_i32 s18, 0xbf
	s_movk_i32 s0, 0x100
	s_cbranch_scc1 .LBB0_2555
	s_add_u32 s19, s74, 0x36400000
	s_addc_u32 s20, s75, 0
	s_add_u32 s21, s74, 0x3b400000
	s_addc_u32 s22, s75, 0
	s_add_u32 s4, s74, 0x2a200000
	s_addc_u32 s5, s75, 0
	s_add_u32 s23, s74, 0x4f700000
	v_lshlrev_b32_e32 v6, 4, v0
	v_readlane_b32 s8, v254, 14
	s_waitcnt lgkmcnt(0)
	v_and_b32_e32 v3, 15, v0
	s_addc_u32 s24, s75, 0
	v_lshrrev_b32_e32 v4, 5, v0
	v_and_b32_e32 v6, 0x1f0, v6
	s_movk_i32 s1, 0x220
	s_add_i32 s6, 0, 0x12e00
	s_lshl_b32 s7, s8, 5
	v_lshlrev_b32_e32 v9, 3, v0
	v_lshrrev_b32_e32 v5, 4, v0
	v_lshl_or_b32 v110, v4, 11, v6
	v_lshlrev_b32_e32 v7, 3, v3
	v_mad_u32_u24 v4, v4, s1, 0
	s_movk_i32 s1, 0x120
	v_mov_b32_e32 v8, s6
	s_add_i32 s6, s6, s7
	v_and_b32_e32 v9, 24, v9
	v_lshrrev_b32_e32 v2, 4, v1
	v_lshl_or_b32 v111, v5, 11, v7
	v_mad_u32_u24 v5, v5, s1, v8
	v_bfe_u32 v8, v0, 2, 2
	v_add_u32_e32 v10, s6, v9
	v_mov_b32_e32 v99, 0
	v_lshlrev_b32_e32 v98, 2, v0
	s_add_i32 s6, 0, 0x17600
	v_lshlrev_b32_e32 v7, 4, v3
	v_lshl_or_b32 v8, v2, 2, v8
	v_and_b32_e32 v11, 48, v0
	v_add_u32_e32 v113, s6, v98
	v_lshl_or_b32 v114, v2, 11, v3
	v_lshl_add_u64 v[2:3], s[74:75], 0, v[98:99]
	s_mov_b64 s[6:7], 0x50f00000
	v_mul_u32_u24_e32 v12, 0x220, v8
	v_mul_u32_u24_e32 v8, 0x120, v8
	s_lshl_b32 s8, s8, 4
	v_lshl_add_u64 v[100:101], v[2:3], 0, s[6:7]
	v_add_u32_e32 v2, 0, v11
	v_cmp_gt_u32_e64 s[0:1], s0, v0
	v_add3_u32 v112, 0, v12, v9
	s_mov_b32 s25, 0x8000
	s_mov_b32 s26, 0x10000
	s_mov_b32 s27, 0x18000
	v_add_u32_e32 v115, v10, v8
	v_add_u32_e32 v116, 0x17600, v2
	s_lshl_b32 s28, s8, 2
	v_lshlrev_b32_e32 v102, 2, v0
	v_add_u32_e32 v117, v4, v6
	v_add_u32_e32 v118, v5, v7
	s_branch .LBB0_2536

.LBB0_2555:
	s_cmp_gt_i32 s77, 21
	s_cselect_b64 s[0:1], -1, 0
	s_and_b64 s[2:3], s[2:3], s[0:1]
	s_andn2_b64 vcc, exec, s[2:3]
	s_cbranch_vccnz .LBB0_2605
	s_mov_b32 vcc_lo, 20
	v_writelane_b32 v255, vcc_lo, 0
	s_branch .Lbar_shared_23
.Lbar_ret_20:
.LBB0_2605:
	s_cmp_lt_i32 s76, 22
	s_cselect_b64 s[2:3], -1, 0
	s_and_b64 s[0:1], s[2:3], s[0:1]
	s_andn2_b64 vcc, exec, s[0:1]
	s_cbranch_vccnz .LBB0_2633
	s_lshl_b32 s0, s33, 2
	s_and_b32 s0, s0, 28
	s_and_b32 s1, s33, 0xffffffe0
	s_or_b32 s0, s0, s1
	s_bfe_u32 s1, s33, 0x20003
	s_or_b32 s0, s0, s1
	s_cmpk_eq_i32 s96, 0x100
	s_cselect_b32 s26, s0, s33
	s_cmpk_gt_i32 s26, 0x4ff
	s_movk_i32 s0, 0x100
	s_cbranch_scc1 .LBB0_2633
	s_add_u32 s27, s74, 0x32400000
	s_addc_u32 s28, s75, 0
	s_add_u32 s29, s74, 0x36400000
	s_addc_u32 s30, s75, 0
	s_add_u32 s31, s74, 0x3a400000
	s_addc_u32 s34, s75, 0
	s_add_u32 s35, s74, 0x3b400000
	s_addc_u32 s36, s75, 0
	s_add_u32 s4, s74, 0x2a200000
	s_addc_u32 s5, s75, 0
	s_add_u32 s37, s74, 0x50f00000
	v_readlane_b32 s10, v254, 14
	s_addc_u32 s38, s75, 0
	s_lshl_b32 s39, s10, 4
	s_lshl_b32 s1, s10, 6
	s_add_u32 s1, s74, s1
	s_addc_u32 s6, s75, 0
	s_add_u32 s42, s1, 0x4f700000
	s_waitcnt lgkmcnt(0)
	v_and_b32_e32 v5, 15, v0
	s_addc_u32 s43, s6, 0
	v_lshrrev_b32_e32 v2, 5, v0
	v_lshlrev_b32_e32 v6, 4, v0
	s_movk_i32 s1, 0x210
	s_add_i32 s8, 0, 0x10c00
	v_lshrrev_b32_e32 v4, 4, v1
	v_lshrrev_b32_e32 v3, 4, v0
	v_and_b32_e32 v190, 0x1f0, v6
	v_lshlrev_b32_e32 v7, 3, v5
	v_mad_u32_u24 v193, v2, s1, 0
	s_add_i32 s6, 0, 0x12e00
	v_lshrrev_b32_e32 v10, 3, v0
	s_movk_i32 s9, 0x88
	v_mov_b32_e32 v11, s8
	v_lshlrev_b32_e32 v189, 2, v4
	v_lshl_or_b32 v191, v2, 11, v190
	v_lshl_or_b32 v192, v3, 11, v7
	v_lshl_add_u32 v7, v2, 4, v193
	s_movk_i32 s1, 0x120
	v_mov_b32_e32 v2, s6
	v_mad_u32_u24 v10, v10, s9, v11
	s_add_i32 s9, 0, 0x17600
	v_bfe_u32 v11, v0, 2, 2
	v_mad_u32_u24 v9, v3, s1, v2
	v_lshlrev_b32_e32 v2, 3, v0
	v_lshl_add_u32 v194, v0, 2, s9
	v_or_b32_e32 v11, v189, v11
	s_lshl_b32 s9, s10, 5
	v_mul_u32_u24_e32 v14, 0x210, v5
	v_lshlrev_b32_e32 v15, 3, v4
	v_lshl_or_b32 v188, v4, 11, v5
	v_lshlrev_b32_e32 v8, 4, v5
	s_add_i32 s6, s6, s9
	v_and_b32_e32 v12, 24, v2
	v_add3_u32 v195, 0, v14, v15
	v_mul_u32_u24_e32 v14, 0x88, v5
	v_lshl_or_b32 v199, v4, 13, v5
	v_and_b32_e32 v4, 48, v0
	v_mul_u32_u24_e32 v5, 0x220, v11
	v_and_b32_e32 v6, 0x70, v6
	v_add_u32_e32 v13, s6, v12
	v_add3_u32 v196, s8, v14, v15
	v_add3_u32 v200, 0, v5, v12
	v_mul_u32_u24_e32 v5, 0x120, v11
	v_lshlrev_b32_e32 v122, 1, v2
	v_add_u32_e32 v2, 0, v4
	s_mov_b32 s7, 0
	v_mov_b32_e32 v3, 0
	v_cmp_gt_u32_e64 s[0:1], s0, v0
	v_add_u32_e32 v197, 32, v195
	v_add_u32_e32 v198, 32, v196
	s_mov_b32 s44, 0x8000
	s_mov_b32 s45, 0x10000
	s_mov_b32 s46, 0x18000
	s_mov_b32 s47, 0x20000
	s_mov_b32 s50, 0x3b600000
	s_lshl_b32 s51, s39, 1
	v_add_u32_e32 v201, v13, v5
	v_add_u32_e32 v202, 0x17600, v2
	s_mov_b32 s54, 0xca00000
	v_add_u32_e32 v203, v7, v190
	v_add_u32_e32 v204, v9, v8
	v_add_u32_e32 v205, v10, v6
	s_branch .LBB0_2609

.LBB0_2633:
	s_cmp_gt_i32 s77, 22
	s_cselect_b64 s[0:1], -1, 0
	s_and_b64 s[2:3], s[2:3], s[0:1]
	s_andn2_b64 vcc, exec, s[2:3]
	s_cbranch_vccnz .LBB0_2683
	s_mov_b32 vcc_lo, 21
	v_writelane_b32 v255, vcc_lo, 0
	s_branch .Lbar_shared_23
.Lbar_ret_21:
.LBB0_2683:
	s_cmp_lt_i32 s76, 23
	s_cselect_b64 s[4:5], -1, 0
	s_and_b64 s[0:1], s[4:5], s[0:1]
	s_andn2_b64 vcc, exec, s[0:1]
	s_cbranch_vccnz .LBB0_2689
	s_lshl_b32 s0, s33, 3
	v_readlane_b32 s1, v254, 14
	s_add_i32 s6, s1, s0
	s_cmpk_gt_i32 s6, 0x3fff
	s_cbranch_scc1 .LBB0_2689
	v_mbcnt_lo_u32_b32 v2, -1, 0
	v_mbcnt_hi_u32_b32 v2, -1, v2
	s_waitcnt lgkmcnt(0)
	v_and_b32_e32 v3, 64, v2
	v_add_u32_e32 v3, 64, v3
	v_xor_b32_e32 v4, 1, v2
	v_cmp_lt_i32_e32 vcc, v4, v3
	v_readlane_b32 s12, v254, 2
	s_ashr_i32 s7, s6, 31
	v_cndmask_b32_e32 v4, v2, v4, vcc
	v_lshlrev_b32_e32 v64, 2, v4
	v_xor_b32_e32 v4, 2, v2
	v_cmp_lt_i32_e32 vcc, v4, v3
	s_lshl_b32 s8, s96, 3
	v_lshlrev_b32_e32 v10, 4, v1
	v_cndmask_b32_e32 v4, v2, v4, vcc
	v_lshlrev_b32_e32 v65, 2, v4
	v_xor_b32_e32 v4, 4, v2
	v_cmp_lt_i32_e32 vcc, v4, v3
	v_mov_b32_e32 v11, 0
	v_readlane_b32 s16, v254, 6
	v_cndmask_b32_e32 v4, v2, v4, vcc
	v_lshlrev_b32_e32 v66, 2, v4
	v_xor_b32_e32 v4, 8, v2
	v_cmp_lt_i32_e32 vcc, v4, v3
	v_readlane_b32 s17, v254, 7
	s_lshl_b64 s[2:3], s[6:7], 2
	v_cndmask_b32_e32 v4, v2, v4, vcc
	v_lshlrev_b32_e32 v67, 2, v4
	v_xor_b32_e32 v4, 16, v2
	v_cmp_lt_i32_e32 vcc, v4, v3
	v_readlane_b32 s18, v254, 8
	v_lshl_add_u64 v[12:13], s[16:17], 0, v[10:11]
	v_cndmask_b32_e32 v4, v2, v4, vcc
	s_add_u32 s17, s2, 0x53000000
	v_lshlrev_b32_e32 v68, 2, v4
	v_xor_b32_e32 v4, 32, v2
	s_addc_u32 s18, s3, 0
	s_lshl_b64 s[2:3], s[6:7], 11
	v_cmp_lt_i32_e32 vcc, v4, v3
	v_lshl_or_b32 v14, v1, 2, s2
	v_mov_b32_e32 v15, s3
	s_lshl_b64 s[2:3], s[6:7], 12
	v_cndmask_b32_e32 v2, v2, v4, vcc
	v_readlane_b32 s13, v254, 3
	v_readlane_b32 s14, v254, 4
	v_readlane_b32 s15, v254, 5
	v_readlane_b32 s19, v254, 9
	s_ashr_i32 s9, s8, 31
	v_lshl_or_b32 v16, v1, 3, s2
	s_mov_b32 s2, 0x358637bd
	v_lshlrev_b32_e32 v69, 2, v2
	v_cmp_eq_u32_e64 s[0:1], 0, v1
	s_lshl_b64 s[10:11], s[8:9], 2
	s_lshl_b64 s[12:13], s[8:9], 11
	v_mov_b32_e32 v17, s3
	s_lshl_b64 s[14:15], s[8:9], 12
	s_mov_b32 s7, 0x2e200000
	s_mov_b32 s16, 0x3b000000
	v_mov_b64_e32 v[18:19], s[2:3]
	s_mov_b32 s9, 0x800000
	s_mov_b32 s19, 0xda24260
	s_mov_b32 s20, 0x42fe0000
	s_mov_b32 s21, 0x40c0c00
	s_mov_b32 s22, 0x51000000
	s_branch .LBB0_2687

.LBB0_2689:
	s_cmp_gt_i32 s77, 23
	s_cselect_b64 s[0:1], -1, 0
	s_and_b64 s[2:3], s[4:5], s[0:1]
	s_andn2_b64 vcc, exec, s[2:3]
	s_cbranch_vccnz .LBB0_2739
	s_mov_b32 vcc_lo, 22
	v_writelane_b32 v255, vcc_lo, 0
	s_branch .Lbar_shared_23
.Lbar_ret_22:
.LBB0_2739:
	s_cmp_lt_i32 s76, 24
	s_cselect_b64 s[6:7], -1, 0
	s_and_b64 s[0:1], s[6:7], s[0:1]
	s_andn2_b64 vcc, exec, s[0:1]
	s_cbranch_vccnz .LBB0_2788
	s_cmpk_lt_i32 s33, 0x200
	s_movk_i32 s2, 0x400
	s_cselect_b64 s[0:1], -1, 0
	s_cmpk_gt_i32 s33, 0x1ff
	v_readfirstlane_b32 s36, v0
	s_cbranch_scc1 .LBB0_2746
	s_ashr_i32 s3, s33, 31
	s_lshr_b32 s3, s3, 29
	s_add_i32 s3, s33, s3
	s_and_b32 s4, s3, -8
	s_sub_i32 s8, s33, s4
	s_cmp_gt_i32 s8, -1
	s_cbranch_scc0 .LBB0_2743
	s_lshl_b32 s9, s8, 6
	s_cbranch_execz .LBB0_2744
	s_branch .LBB0_2745

.LBB0_2788:
	s_cmp_gt_i32 s77, 24
	s_cselect_b64 s[0:1], -1, 0
	s_and_b64 s[2:3], s[6:7], s[0:1]
	s_andn2_b64 vcc, exec, s[2:3]
	s_cbranch_vccnz .LBB0_2838
	s_mov_b32 vcc_lo, 23
	v_writelane_b32 v255, vcc_lo, 0

.LBB0_2837:
	s_or_b64 exec, exec, s[2:3]
	s_waitcnt lgkmcnt(0)
	s_barrier
	v_readlane_b32 vcc_lo, v255, 0
	s_nop 3
	s_cmp_eq_u32 vcc_lo, 19
	s_cbranch_scc1 .Lbar_ret_19
	s_cmp_eq_u32 vcc_lo, 20
	s_cbranch_scc1 .Lbar_ret_20
	s_cmp_eq_u32 vcc_lo, 21
	s_cbranch_scc1 .Lbar_ret_21
	s_cmp_eq_u32 vcc_lo, 22
	s_cbranch_scc1 .Lbar_ret_22
	s_cmp_eq_u32 vcc_lo, 24
	s_cbranch_scc1 .Lbar_ret_24
	s_cmp_eq_u32 vcc_lo, 25
	s_cbranch_scc1 .Lbar_ret_25
	s_cmp_eq_u32 vcc_lo, 26
	s_cbranch_scc1 .Lbar_ret_26
	s_cmp_eq_u32 vcc_lo, 27
	s_cbranch_scc1 .Lbar_ret_27

.LBB0_2876:
	s_cmp_gt_i32 s77, 25
	s_cselect_b64 s[0:1], -1, 0
	s_and_b64 s[2:3], s[12:13], s[0:1]
	s_andn2_b64 vcc, exec, s[2:3]
	s_cbranch_vccnz .LBB0_2926
	s_mov_b32 vcc_lo, 24
	v_writelane_b32 v255, vcc_lo, 0
	s_branch .Lbar_shared_23
.Lbar_ret_24:
.LBB0_2926:
	s_cmp_lt_i32 s76, 26
	s_cselect_b64 s[4:5], -1, 0
	s_and_b64 s[0:1], s[4:5], s[0:1]
	s_andn2_b64 vcc, exec, s[0:1]
	s_cbranch_vccnz .LBB0_2957
	s_movk_i32 s0, 0x400
	s_cmpk_gt_i32 s33, 0x7ff
	v_readfirstlane_b32 s22, v0
	s_cbranch_scc1 .LBB0_2957
	s_ashr_i32 s36, s33, 31
	s_lshr_b32 s1, s36, 29
	s_add_i32 s1, s33, s1
	s_and_b32 s2, s1, -8
	s_sub_i32 s6, s33, s2
	s_cmp_gt_i32 s6, -1
	s_cbranch_scc0 .LBB0_2930
	s_lshl_b32 s10, s6, 8
	s_cbranch_execz .LBB0_2931
	s_branch .LBB0_2932

.LBB0_2957:
	s_cmp_gt_i32 s77, 26
	s_cselect_b64 s[0:1], -1, 0
	s_and_b64 s[2:3], s[4:5], s[0:1]
	s_andn2_b64 vcc, exec, s[2:3]
	s_cbranch_vccnz .LBB0_3007
	s_mov_b32 vcc_lo, 25
	v_writelane_b32 v255, vcc_lo, 0
	s_branch .Lbar_shared_23
.Lbar_ret_25:
.LBB0_3007:
	s_cmp_lt_i32 s76, 27
	s_cselect_b64 s[6:7], -1, 0
	s_and_b64 s[0:1], s[6:7], s[0:1]
	s_andn2_b64 vcc, exec, s[0:1]
	s_cbranch_vccnz .LBB0_3055
	s_cmpk_lt_i32 s33, 0x200
	s_movk_i32 s0, 0x2000
	s_cselect_b64 s[2:3], -1, 0
	s_cmpk_gt_i32 s33, 0x1ff
	v_readfirstlane_b32 s28, v0
	s_cbranch_scc1 .LBB0_3014
	s_ashr_i32 s1, s33, 31
	s_lshr_b32 s1, s1, 29
	s_add_i32 s1, s33, s1
	s_and_b32 s4, s1, -8
	s_sub_i32 s8, s33, s4
	s_cmp_gt_i32 s8, -1
	s_cbranch_scc0 .LBB0_3011
	s_lshl_b32 s9, s8, 6
	s_cbranch_execz .LBB0_3012
	s_branch .LBB0_3013

.LBB0_3055:
	s_cmp_gt_i32 s77, 27
	s_cselect_b64 s[0:1], -1, 0
	s_and_b64 s[2:3], s[6:7], s[0:1]
	s_andn2_b64 vcc, exec, s[2:3]
	s_cbranch_vccnz .LBB0_3105
	s_mov_b32 vcc_lo, 26
	v_writelane_b32 v255, vcc_lo, 0
	s_branch .Lbar_shared_23
.Lbar_ret_26:
.LBB0_3105:
	s_cmp_lt_i32 s76, 28
	s_cselect_b64 s[14:15], -1, 0
	s_and_b64 s[0:1], s[14:15], s[0:1]
	s_andn2_b64 vcc, exec, s[0:1]
	s_cbranch_vccnz .LBB0_3365
	s_cmpk_lt_i32 s33, 0x300
	s_movk_i32 s2, 0x800
	s_cselect_b64 s[4:5], -1, 0
	s_cmpk_gt_i32 s33, 0x2ff
	s_mov_b32 s60, -1
	s_cbranch_scc1 .LBB0_3108
	s_ashr_i32 s0, s33, 31
	s_lshr_b32 s0, s0, 29
	s_add_i32 s0, s33, s0
	s_ashr_i32 s1, s0, 3
	s_and_b32 s0, s0, -8
	s_sub_i32 s0, s33, s0
	s_cmp_lt_i32 s0, 0
	s_movk_i32 s3, 0x61
	s_cselect_b32 s3, s3, 0x60
	s_mul_i32 s0, s0, s3
	s_add_i32 s0, s0, s1
	s_mul_hi_i32 s1, s0, 0x2aaaaaab
	s_lshr_b32 s3, s1, 31
	s_ashr_i32 s1, s1, 4
	s_add_i32 s1, s1, s3
	s_lshl_b32 s3, s1, 3
	s_mulk_i32 s1, 0x60
	s_sub_i32 s0, s0, s1
	s_bfe_i32 s1, s0, 0x80000
	s_bfe_u32 s1, s1, 0x3000c
	s_add_i32 s1, s0, s1
	s_and_b32 s1, s1, 0xf8
	s_sub_i32 s0, s0, s1
	s_sext_i32_i8 s0, s0
	s_add_i32 s60, s3, s0

.LBB0_3365:
	s_cmp_gt_i32 s77, 28
	s_cselect_b64 s[0:1], -1, 0
	s_and_b64 s[2:3], s[14:15], s[0:1]
	s_andn2_b64 vcc, exec, s[2:3]
	s_cbranch_vccnz .LBB0_3415
	s_mov_b32 vcc_lo, 27
	v_writelane_b32 v255, vcc_lo, 0
	s_branch .Lbar_shared_23
.Lbar_ret_27:
.LBB0_3415:
	s_cmp_lt_i32 s76, 29
	s_cselect_b64 s[4:5], -1, 0
	s_and_b64 s[0:1], s[4:5], s[0:1]
	s_andn2_b64 vcc, exec, s[0:1]
	s_cbranch_vccnz .LBB0_3464
	s_cmpk_gt_i32 s33, 0x1ff
	s_cbranch_scc1 .LBB0_3464
	s_add_u32 s26, s74, 0x26200000
	s_addc_u32 s27, s75, 0
	s_add_u32 s28, s74, 0x2a200000
	s_addc_u32 s29, s75, 0
	s_add_u32 s30, s74, 0x2b200000
	s_addc_u32 s31, s75, 0
	s_add_u32 s34, s74, 0x22200000
	s_addc_u32 s35, s75, 0
	s_add_u32 s20, s74, 0x15f00000
	s_addc_u32 s21, s75, 0
	s_waitcnt lgkmcnt(0)
	v_lshrrev_b32_e32 v3, 6, v0
	v_lshrrev_b32_e32 v13, 4, v1
	s_mov_b64 s[2:3], src_shared_base
	s_add_u32 s22, s74, 0x16100000
	v_lshl_or_b32 v13, v3, 2, v13
	s_addc_u32 s23, s75, 0
	v_lshlrev_b32_e32 v10, 4, v0
	v_lshlrev_b32_e32 v14, 10, v13
	v_lshlrev_b32_e32 v13, 4, v13
	s_add_i32 s2, 0, 0x1e000
	v_and_b32_e32 v155, 31, v0
	v_and_b32_e32 v7, 0x1c0, v0
	v_and_b32_e32 v15, 0xf0, v10
	v_and_b32_e32 v13, 0x70, v13
	s_cmp_lg_u32 0, -1
	v_lshl_or_b32 v8, v3, 5, v155
	s_waitcnt vmcnt(0)
	v_bitop3_b32 v132, v13, v14, v15 bitop3:0xde
	v_lshrrev_b32_e32 v13, 4, v0
	v_lshlrev_b32_e32 v140, 10, v3
	v_lshlrev_b32_e32 v159, 16, v3
	v_lshl_add_u32 v3, v7, 2, s2
	s_cselect_b32 s2, 0, 0
	v_and_b32_e32 v13, 16, v13
	v_lshrrev_b32_e32 v15, 1, v0
	v_lshrrev_b32_e32 v16, 5, v0
	s_cselect_b32 s3, s3, 0
	s_add_u32 s2, s2, 0xc000
	v_lshrrev_b32_e32 v5, 5, v1
	v_lshlrev_b32_e32 v9, 3, v0
	v_bfe_u32 v14, v0, 2, 2
	v_and_b32_e32 v15, 8, v15
	v_and_or_b32 v13, v16, 4, v13
	s_addc_u32 s3, s3, 0
	v_and_b32_e32 v11, 0xc0, v10
	v_lshlrev_b32_e32 v12, 1, v0
	v_or3_b32 v13, v13, v14, v15
	v_and_or_b32 v14, v16, 2, v5
	v_and_b32_e32 v15, 48, v10
	v_and_b32_e32 v157, 0x118, v9
	v_lshlrev_b32_e32 v142, 4, v5
	v_lshlrev_b32_e32 v9, 2, v5
	s_cmp_lg_u64 s[2:3], 0
	v_lshlrev_b32_e32 v4, 11, v8
	v_mov_b32_e32 v2, 0
	v_lshlrev_b32_e32 v6, 3, v5
	v_lshl_or_b32 v14, v14, 6, v15
	v_lshlrev_b32_e32 v156, 8, v155
	v_and_or_b32 v158, v12, 32, v11
	v_lshlrev_b32_e32 v5, 13, v5
	v_add_u32_e32 v151, 0, v140
	s_cselect_b32 s2, s2, -1
	v_lshl_add_u32 v153, v155, 2, v3
	v_add_u32_e32 v154, v3, v142
	v_sub_u32_e32 v3, v8, v9
	v_lshl_or_b32 v134, v13, 10, v14
	v_mov_b32_e32 v133, v2
	v_mov_b32_e32 v135, v2
	v_and_b32_e32 v141, 0x70, v10
	v_or_b32_e32 v143, 64, v142
	v_or_b32_e32 v144, 0x80, v142
	v_or_b32_e32 v145, 0xc0, v142
	v_cmp_gt_u32_e64 s[0:1], 32, v1
	v_or_b32_e32 v146, 32, v142
	v_or_b32_e32 v147, 0x60, v142
	v_or_b32_e32 v148, 0xa0, v142
	v_or_b32_e32 v149, 0xe0, v142
	v_or3_b32 v150, v5, v159, v155
	v_add_u32_e32 v152, s2, v156
	v_add3_u32 v160, v157, 0, v158
	v_add_u32_e32 v161, 0x144, v3
	s_lshl_b32 s24, s33, 4
	s_lshl_b32 s25, s96, 4
	v_lshlrev_b32_e32 v138, 1, v4
	v_mov_b32_e32 v139, v2
	v_lshlrev_b32_e32 v136, 1, v6
	v_mov_b32_e32 v137, v2
	v_add_u32_e32 v162, 0xc000, v151
	s_mov_b64 s[6:7], 0x8000
	v_add_u32_e32 v163, 0xe000, v151
	v_add_u32_e32 v164, 0x2000, v151
	s_mov_b64 s[8:9], 0x10000
	s_mov_b64 s[10:11], 0x18000
	s_add_i32 s36, 0, 0x10000
	s_add_i32 s37, 0, 0x12000
	s_movk_i32 s38, 0xfefe
	s_mov_b32 s39, 0x42b504f3
	s_mov_b32 s40, 0x3fb8aa3b
	s_movk_i32 s41, 0x7fff
	v_mov_b32_e32 v165, 0xf149f2ca
	s_mov_b32 s42, s33
	s_branch .LBB0_3420

.LBB0_3464:
	s_cmp_gt_i32 s77, 29
	s_cselect_b64 s[0:1], -1, 0
	s_and_b64 s[2:3], s[4:5], s[0:1]
	s_andn2_b64 vcc, exec, s[2:3]
	v_readlane_b32 s50, v254, 13
	s_cbranch_vccnz .LBB0_3514
	s_mov_b32 vcc_lo, 28
	v_writelane_b32 v255, vcc_lo, 0
	s_branch .Lbar_shared_30
.Lbar_ret_28:
.LBB0_3514:
	s_cmp_lt_i32 s76, 30
	s_cselect_b64 s[2:3], -1, 0
	s_and_b64 s[0:1], s[2:3], s[0:1]
	s_andn2_b64 vcc, exec, s[0:1]
	s_cbranch_vccnz .LBB0_3538
	s_lshl_b32 s0, s33, 3
	v_readlane_b32 s1, v254, 14
	s_add_i32 s16, s1, s0
	s_cmpk_gt_i32 s16, 0x3fff
	s_cbranch_scc1 .LBB0_3538
	v_mov_b32_e32 v67, 0
	v_lshlrev_b32_e32 v2, 4, v1
	s_waitcnt lgkmcnt(0)
	v_mov_b32_e32 v3, v67
	v_lshlrev_b32_e32 v66, 3, v1
	v_lshl_add_u64 v[2:3], s[74:75], 0, v[2:3]
	s_mov_b64 s[0:1], 0x22200000
	v_lshl_add_u64 v[68:69], v[2:3], 0, s[0:1]
	v_lshl_add_u64 v[2:3], s[74:75], 0, v[66:67]
	s_mov_b64 s[4:5], 0x51000000
	s_waitcnt vmcnt(0)
	v_lshl_add_u64 v[70:71], v[2:3], 0, s[4:5]
	v_mbcnt_lo_u32_b32 v2, -1, 0
	v_mbcnt_hi_u32_b32 v2, -1, v2
	v_and_b32_e32 v3, 64, v2
	v_add_u32_e32 v3, 64, v3
	v_xor_b32_e32 v4, 1, v2
	v_cmp_lt_i32_e32 vcc, v4, v3
	s_lshl_b32 s20, s96, 3
	s_add_u32 s21, s74, 0x53000000
	v_cndmask_b32_e32 v4, v2, v4, vcc
	v_lshlrev_b32_e32 v66, 2, v4
	v_xor_b32_e32 v4, 2, v2
	v_cmp_lt_i32_e32 vcc, v4, v3
	s_addc_u32 s22, s75, 0
	v_cmp_eq_u32_e64 s[0:1], 0, v1
	v_cndmask_b32_e32 v4, v2, v4, vcc
	v_lshlrev_b32_e32 v72, 2, v4
	v_xor_b32_e32 v4, 4, v2
	v_cmp_lt_i32_e32 vcc, v4, v3
	s_lshl_b32 s23, s96, 4
	s_mul_i32 s24, s96, 24
	v_cndmask_b32_e32 v4, v2, v4, vcc
	v_lshlrev_b32_e32 v73, 2, v4
	v_xor_b32_e32 v4, 8, v2
	v_cmp_lt_i32_e32 vcc, v4, v3
	s_mov_b32 s25, 0xda24260
	s_mov_b32 s26, 0x42fe0000
	v_cndmask_b32_e32 v4, v2, v4, vcc
	v_lshlrev_b32_e32 v74, 2, v4
	v_xor_b32_e32 v4, 16, v2
	v_cmp_lt_i32_e32 vcc, v4, v3
	s_mov_b32 s27, 0x40c0c00
	s_nop 0
	v_cndmask_b32_e32 v4, v2, v4, vcc
	v_lshlrev_b32_e32 v75, 2, v4
	v_xor_b32_e32 v4, 32, v2
	v_cmp_lt_i32_e32 vcc, v4, v3
	s_nop 1
	v_cndmask_b32_e32 v2, v2, v4, vcc
	v_lshlrev_b32_e32 v76, 2, v2
	s_branch .LBB0_3519

.LBB0_3538:
	s_cmp_gt_i32 s77, 30
	s_cselect_b64 s[0:1], -1, 0
	s_and_b64 s[2:3], s[2:3], s[0:1]
	s_andn2_b64 vcc, exec, s[2:3]
	s_cbranch_vccnz .LBB0_3588
	s_mov_b32 vcc_lo, 29
	v_writelane_b32 v255, vcc_lo, 0
	s_branch .Lbar_shared_30
.Lbar_ret_29:
.LBB0_3588:
	s_cmp_lt_i32 s76, 31
	s_cselect_b64 s[6:7], -1, 0
	s_and_b64 s[0:1], s[6:7], s[0:1]
	s_andn2_b64 vcc, exec, s[0:1]
	s_cbranch_vccnz .LBB0_3637
	s_cmpk_lt_i32 s33, 0x200
	s_movk_i32 s2, 0x400
	s_cselect_b64 s[0:1], -1, 0
	s_cmpk_gt_i32 s33, 0x1ff
	v_readfirstlane_b32 s36, v0
	s_cbranch_scc1 .LBB0_3595
	s_ashr_i32 s3, s33, 31
	s_lshr_b32 s3, s3, 29
	s_add_i32 s3, s33, s3
	s_and_b32 s4, s3, -8
	s_sub_i32 s8, s33, s4
	s_cmp_gt_i32 s8, -1
	s_cbranch_scc0 .LBB0_3592
	s_lshl_b32 s9, s8, 6
	s_cbranch_execz .LBB0_3593
	s_branch .LBB0_3594

.LBB0_3637:
	s_cmp_gt_i32 s77, 31
	s_cselect_b64 s[0:1], -1, 0
	s_and_b64 s[2:3], s[6:7], s[0:1]
	s_andn2_b64 vcc, exec, s[2:3]
	s_cbranch_vccnz .LBB0_3687
	s_mov_b32 vcc_lo, 30
	v_writelane_b32 v255, vcc_lo, 0
.Lbar_shared_30:
	s_waitcnt vmcnt(0)
	v_cmp_eq_u32_e32 vcc, 0, v0
	s_waitcnt vmcnt(0) lgkmcnt(0)
	s_barrier
	s_and_saveexec_b64 s[2:3], vcc
	s_cbranch_execz .LBB0_3686
	v_mov_b32_e32 v2, s50
	s_waitcnt vmcnt(0) expcnt(0) lgkmcnt(0)
	ds_read_b32 v4, v2
	ds_read_b32 v2, v2 offset:4
	s_waitcnt lgkmcnt(1)
	v_cmp_ne_u32_e32 vcc, 0, v4
	s_cbranch_vccnz .LBB0_3654
	v_readlane_b32 s4, v254, 11
	v_readlane_b32 s5, v254, 12
	s_load_dwordx2 s[8:9], s[4:5], 0x4
	s_add_u32 s4, s78, 0x1000
	s_addc_u32 s5, s79, 0
	s_add_u32 s6, s78, 0x1100
	s_addc_u32 s7, s79, 0
	s_waitcnt lgkmcnt(0)
	s_mul_i32 s18, s8, s96
	s_add_u32 s8, s78, 0x1200
	s_mul_i32 s18, s18, s9
	s_addc_u32 s9, s79, 0
	s_add_u32 s10, s78, 0x1300
	s_addc_u32 s11, s79, 0
	s_mov_b32 s19, 1
	v_mov_b32_e32 v18, 0
	s_branch .LBB0_3642

.LBB0_3686:
	s_or_b64 exec, exec, s[2:3]
	s_waitcnt lgkmcnt(0)
	s_barrier
	v_readlane_b32 vcc_lo, v255, 0
	s_nop 3
	s_cmp_eq_u32 vcc_lo, 28
	s_cbranch_scc1 .Lbar_ret_28
	s_cmp_eq_u32 vcc_lo, 29
	s_cbranch_scc1 .Lbar_ret_29
	s_cmp_eq_u32 vcc_lo, 31
	s_cbranch_scc1 .Lbar_ret_31
	s_cmp_eq_u32 vcc_lo, 32
	s_cbranch_scc1 .Lbar_ret_32

.LBB0_3725:
	s_cmp_gt_i32 s77, 32
	s_cselect_b64 s[0:1], -1, 0
	s_and_b64 s[2:3], s[12:13], s[0:1]
	s_andn2_b64 vcc, exec, s[2:3]
	s_cbranch_vccnz .LBB0_3775
	s_mov_b32 vcc_lo, 31
	v_writelane_b32 v255, vcc_lo, 0
	s_branch .Lbar_shared_30
.Lbar_ret_31:
.LBB0_3775:
	s_cmp_lt_i32 s76, 33
	s_cselect_b64 s[4:5], -1, 0
	s_and_b64 s[0:1], s[4:5], s[0:1]
	s_andn2_b64 vcc, exec, s[0:1]
	s_cbranch_vccnz .LBB0_3806
	s_movk_i32 s0, 0x400
	s_cmpk_gt_i32 s33, 0x7ff
	v_readfirstlane_b32 s22, v0
	s_cbranch_scc1 .LBB0_3806
	s_ashr_i32 s36, s33, 31
	s_lshr_b32 s1, s36, 29
	s_add_i32 s1, s33, s1
	s_and_b32 s2, s1, -8
	s_sub_i32 s6, s33, s2
	s_cmp_gt_i32 s6, -1
	s_cbranch_scc0 .LBB0_3779
	s_lshl_b32 s10, s6, 8
	s_cbranch_execz .LBB0_3780
	s_branch .LBB0_3781

.LBB0_3806:
	s_cmp_gt_i32 s77, 33
	s_cselect_b64 s[0:1], -1, 0
	s_and_b64 s[2:3], s[4:5], s[0:1]
	s_andn2_b64 vcc, exec, s[2:3]
	s_cbranch_vccnz .LBB0_3856
	s_mov_b32 vcc_lo, 32
	v_writelane_b32 v255, vcc_lo, 0
	s_branch .Lbar_shared_30
.Lbar_ret_32:
.LBB0_3856:
	s_cmp_lt_i32 s76, 34
	s_cselect_b64 s[4:5], -1, 0
	s_and_b64 s[0:1], s[4:5], s[0:1]
	s_andn2_b64 vcc, exec, s[0:1]
	s_cbranch_vccnz .LBB0_3886
	s_movk_i32 s0, 0x2000
	s_cmpk_gt_i32 s33, 0x1ff
	v_readfirstlane_b32 s18, v0
	s_cbranch_scc1 .LBB0_3886
	s_ashr_i32 s30, s33, 31
	s_lshr_b32 s1, s30, 29
	s_add_i32 s6, s33, s1
	s_and_b32 s1, s6, -8
	s_sub_i32 s1, s33, s1
	s_cmp_gt_i32 s1, -1
	s_cbranch_scc0 .LBB0_3860
	s_lshl_b32 s10, s1, 6
	s_ashr_i32 s2, s6, 3
	s_cbranch_execz .LBB0_3861
	s_branch .LBB0_3862

	.amdhsa_kernel _Z6mk_fwd4Args
		.amdhsa_group_segment_fixed_size 0
		.amdhsa_private_segment_fixed_size 0
		.amdhsa_kernarg_size 560
		.amdhsa_user_sgpr_count 2
		.amdhsa_user_sgpr_dispatch_ptr 0
		.amdhsa_user_sgpr_queue_ptr 0
		.amdhsa_user_sgpr_kernarg_segment_ptr 1
		.amdhsa_user_sgpr_dispatch_id 0
		.amdhsa_user_sgpr_kernarg_preload_length 0
		.amdhsa_user_sgpr_kernarg_preload_offset 0
		.amdhsa_user_sgpr_private_segment_size 0
		.amdhsa_uses_dynamic_stack 0
		.amdhsa_enable_private_segment 0
		.amdhsa_system_sgpr_workgroup_id_x 1
		.amdhsa_system_sgpr_workgroup_id_y 0
		.amdhsa_system_sgpr_workgroup_id_z 0
		.amdhsa_system_sgpr_workgroup_info 0
		.amdhsa_system_vgpr_workitem_id 0
		.amdhsa_next_free_vgpr 256
		.amdhsa_next_free_sgpr 98
		.amdhsa_accum_offset 256
		.amdhsa_reserve_vcc 1
		.amdhsa_float_round_mode_32 0
		.amdhsa_float_round_mode_16_64 0
		.amdhsa_float_denorm_mode_32 3
		.amdhsa_float_denorm_mode_16_64 3
		.amdhsa_dx10_clamp 1
		.amdhsa_ieee_mode 1
		.amdhsa_fp16_overflow 0
		.amdhsa_tg_split 0
		.amdhsa_exception_fp_ieee_invalid_op 0
		.amdhsa_exception_fp_denorm_src 0
		.amdhsa_exception_fp_ieee_div_zero 0
		.amdhsa_exception_fp_ieee_overflow 0
		.amdhsa_exception_fp_ieee_underflow 0
		.amdhsa_exception_fp_ieee_inexact 0
		.amdhsa_exception_int_div_zero 0
	.end_amdhsa_kernel

amdhsa.kernels:
  - .agpr_count:     0
    .args:
      - .offset:         0
        .size:           304
        .value_kind:     by_value
      - .offset:         304
        .size:           4
        .value_kind:     hidden_block_count_x
      - .offset:         308
        .size:           4
        .value_kind:     hidden_block_count_y
      - .offset:         312
        .size:           4
        .value_kind:     hidden_block_count_z
      - .offset:         316
        .size:           2
        .value_kind:     hidden_group_size_x
      - .offset:         318
        .size:           2
        .value_kind:     hidden_group_size_y
      - .offset:         320
        .size:           2
        .value_kind:     hidden_group_size_z
      - .offset:         322
        .size:           2
        .value_kind:     hidden_remainder_x
      - .offset:         324
        .size:           2
        .value_kind:     hidden_remainder_y
      - .offset:         326
        .size:           2
        .value_kind:     hidden_remainder_z
      - .offset:         344
        .size:           8
        .value_kind:     hidden_global_offset_x
      - .offset:         352
        .size:           8
        .value_kind:     hidden_global_offset_y
      - .offset:         360
        .size:           8
        .value_kind:     hidden_global_offset_z
      - .offset:         368
        .size:           2
        .value_kind:     hidden_grid_dims
      - .offset:         424
        .size:           4
        .value_kind:     hidden_dynamic_lds_size
    .group_segment_fixed_size: 0
    .kernarg_segment_align: 8
    .kernarg_segment_size: 560
    .language:       OpenCL C
    .language_version:
      - 2
      - 0
    .max_flat_workgroup_size: 512
    .name:           _Z6mk_fwd4Args
    .private_segment_fixed_size: 0
    .sgpr_count:     104
    .sgpr_spill_count: 41
    .symbol:         _Z6mk_fwd4Args.kd
    .uniform_work_group_size: 1
    .uses_dynamic_stack: false
    .vgpr_count:     256
    .vgpr_spill_count: 0
    .wavefront_size: 64
